# MLA fast loop: all 12 next-tile K fragments read before the step barrier into spare VGPRs, K staged one tile ahead, restage ds_writes in QK region, first QK MFMA hoisted to step top
# baseline (speedup 1.0000x reference)
; #define LAS __attribute__((address_space(3)))
; template <int DK>
; __device__ __forceinline__ void attn_unit(LAS unsigned char* lds, const bf16_t* Qp, int qpitch, const bf16_t* Kp, int kpitch, const bf16_t* Vp, int vpitch, bf16_t* Op, int nt) {
;     ...
;     __syncthreads();
;     f32x16 o0, o1, cA0, cA1, cB0, cB1;
; #pragma unroll
;     for (int i = 0; i < 16; ++i) { o0[i] = 0.f; o1[i] = 0.f; cA0[i] = 0.f; cA1[i] = 0.f; }
; #pragma unroll
;     for (int ds = 0; ds < NDS; ++ds) {
;         const bf16x8 a0 = *(const LAS bf16x8*)(lds + aoffk + ds * 32);
;         const bf16x8 a1 = *(const LAS bf16x8*)(lds + aoffk + 32 * KSTR + ds * 32);
;         cA0 = __builtin_amdgcn_mfma_f32_32x32x16_bf16(a0, qf[ds], cA0, 0, 0, 0);
;         cA1 = __builtin_amdgcn_mfma_f32_32x32x16_bf16(a1, qf[ds], cA1, 0, 0, 0);
;     }
; #pragma unroll
;     for (int i = 0; i < 16; ++i) { cA0[i] = __builtin_amdgcn_exp2f(cA0[i]); cA1[i] = __builtin_amdgcn_exp2f(cA1[i]); }
;     __syncthreads();
;     float l = 0.f;
;     int t = 0;
;     ...
;     for (; t + 4 < nt; t += 2) {
;         attn_step<DK, 0, true, true, true, true>(ATT_EVEN(cA0, cA1, cB0, cB1, t));
;         attn_step<DK, 1, true, true, true, true>(ATT_ODD(cB0, cB1, cA0, cA1, t + 1));
;     }
.LBB0_761:
	s_or_b64 exec, exec, s[16:17]
	v_and_b32_e32 v0, 31, v36
	v_mul_u32_u24_e32 v0, 0xd0, v0
	s_mov_b32 s16, 0x18000
	v_lshl_add_u32 v2, v37, 4, v0
	v_add_co_u32_e32 v0, vcc, s16, v158
	v_add_u32_e32 v181, 0, v2
	s_nop 0
	v_addc_co_u32_e32 v1, vcc, 0, v159, vcc
	global_load_dwordx4 v[136:139], v[0:1], off
	s_waitcnt lgkmcnt(0)
	s_barrier
	ds_read_b128 v[0:3], v181
	ds_read_b128 v[42:45], v181 offset:32
	s_waitcnt vmcnt(2) lgkmcnt(1)
	v_mfma_f32_32x32x16_bf16 v[0:15], v[0:3], v[120:123], 0
	ds_read_b128 v[16:19], v181 offset:6656
	ds_read_b128 v[46:49], v181 offset:6688
	s_movk_i32 s18, 0x480
	v_mad_i64_i32 v[40:41], s[16:17], v40, s18, 0
	v_lshlrev_b32_e32 v171, 3, v37
	v_mov_b64_e32 v[126:127], v[98:99]
	v_ashrrev_i32_e32 v149, 31, v148
	s_waitcnt lgkmcnt(1)
	v_mfma_f32_32x32x16_bf16 v[16:31], v[16:19], v[120:123], 0
	v_mov_b64_e32 v[124:125], v[96:97]
	v_mfma_f32_32x32x16_bf16 v[0:15], v[42:45], v[116:119], v[0:15]
	s_waitcnt lgkmcnt(0)
	v_mfma_f32_32x32x16_bf16 v[16:31], v[46:49], v[116:119], v[16:31]
	ds_read_b128 v[42:45], v181 offset:64
	ds_read_b128 v[46:49], v181 offset:96
	s_waitcnt lgkmcnt(1)
	v_mfma_f32_32x32x16_bf16 v[0:15], v[42:45], v[112:115], v[0:15]
	ds_read_b128 v[42:45], v181 offset:6720
	ds_read_b128 v[50:53], v181 offset:6752
	s_waitcnt lgkmcnt(2)
	v_mfma_f32_32x32x16_bf16 v[0:15], v[46:49], v[108:111], v[0:15]
	s_waitcnt lgkmcnt(1)
	v_mfma_f32_32x32x16_bf16 v[16:31], v[42:45], v[112:115], v[16:31]
	ds_read_b128 v[42:45], v181 offset:128
	ds_read_b128 v[46:49], v181 offset:160
	s_waitcnt lgkmcnt(1)
	v_mfma_f32_32x32x16_bf16 v[0:15], v[42:45], v[104:107], v[0:15]
	ds_read_b128 v[42:45], v181 offset:6784
	v_mfma_f32_32x32x16_bf16 v[16:31], v[50:53], v[108:111], v[16:31]
	ds_read_b128 v[50:53], v181 offset:6816
	s_waitcnt lgkmcnt(0)
	s_barrier
	v_mfma_f32_32x32x16_bf16 v[16:31], v[42:45], v[104:107], v[16:31]
	v_mad_i64_i32 v[42:43], s[16:17], v38, s18, 0
	v_bfe_u32 v44, v36, 2, 2
	v_mad_i64_i32 v[38:39], s[16:17], v39, s60, 0
	v_lshl_or_b32 v37, v37, 2, v44
	v_and_b32_e32 v44, 16, v36
	v_mfma_f32_32x32x16_bf16 v[0:15], v[46:49], v[100:103], v[0:15]
	v_lshlrev_b32_e32 v45, 2, v36
	v_mul_u32_u24_e32 v37, 0xc0, v37
	v_and_or_b32 v44, v45, 12, v44
	v_lshl_or_b32 v37, v44, 1, v37
	v_mov_b32_e32 v48, 0
	v_add_u32_e32 v172, 0, v37
	s_nop 5
	v_exp_f32_e32 v185, v0
	v_mfma_f32_32x32x16_bf16 v[16:31], v[50:53], v[100:103], v[16:31]
	v_exp_f32_e32 v187, v1
	v_lshl_add_u64 v[0:1], s[70:71], 0, v[42:43]
	v_lshl_add_u64 v[0:1], v[32:33], 1, v[0:1]
	v_lshl_add_u64 v[164:165], v[0:1], 0, s[12:13]
	v_lshl_add_u64 v[0:1], s[70:71], 0, v[40:41]
	v_exp_f32_e32 v186, v2
	v_exp_f32_e32 v189, v3
	s_nop 4
	v_exp_f32_e32 v183, v16
	v_exp_f32_e32 v184, v17
	v_exp_f32_e32 v82, v18
	v_exp_f32_e32 v83, v19
	v_exp_f32_e32 v188, v4
	v_exp_f32_e32 v84, v20
	v_exp_f32_e32 v190, v5
	v_exp_f32_e32 v85, v21
	v_exp_f32_e32 v192, v6
	v_exp_f32_e32 v86, v22
	v_exp_f32_e32 v194, v7
	v_exp_f32_e32 v87, v23
	v_exp_f32_e32 v191, v8
	v_exp_f32_e32 v72, v24
	v_exp_f32_e32 v193, v9
	v_exp_f32_e32 v73, v25
	v_exp_f32_e32 v88, v10
	v_exp_f32_e32 v74, v26
	v_exp_f32_e32 v90, v11
	v_exp_f32_e32 v75, v27
	v_exp_f32_e32 v89, v12
	v_exp_f32_e32 v76, v28
	v_exp_f32_e32 v91, v13
	v_exp_f32_e32 v77, v29
	v_exp_f32_e32 v92, v14
	v_exp_f32_e32 v78, v30
	v_exp_f32_e32 v93, v15
	v_exp_f32_e32 v79, v31
	v_lshl_add_u64 v[0:1], v[34:35], 1, v[0:1]
	v_and_b32_e32 v2, 7, v36
	v_lshl_add_u64 v[166:167], v[0:1], 0, s[12:13]
	v_lshl_add_u64 v[0:1], s[10:11], 0, v[38:39]
	v_lshlrev_b32_e32 v2, 4, v2
	v_mov_b32_e32 v3, v97
	v_lshl_add_u64 v[0:1], v[0:1], 0, v[2:3]
	v_lshl_add_u64 v[168:169], s[14:15], 1, v[0:1]
	s_mov_b32 s12, -2
	v_mov_b32_e32 v0, 0
	v_mov_b32_e32 v1, v48
	v_mov_b32_e32 v2, v48
	v_mov_b32_e32 v3, v48
	v_mov_b32_e32 v4, v48
	v_mov_b32_e32 v5, v48
	v_mov_b32_e32 v6, v48
	v_mov_b32_e32 v7, v48
	v_mov_b32_e32 v8, v48
	v_mov_b32_e32 v9, v48
	v_mov_b32_e32 v10, v48
	v_mov_b32_e32 v11, v48
	v_mov_b32_e32 v12, v48
	v_mov_b32_e32 v13, v48
	v_mov_b32_e32 v14, v48
	v_mov_b32_e32 v15, v48
	v_mov_b32_e32 v16, 0
	v_mov_b32_e32 v17, v48
	v_mov_b32_e32 v18, v48
	v_mov_b32_e32 v19, v48
	v_mov_b32_e32 v20, v48
	v_mov_b32_e32 v21, v48
	v_mov_b32_e32 v22, v48
	v_mov_b32_e32 v23, v48
	v_mov_b32_e32 v24, v48
	v_mov_b32_e32 v25, v48
	v_mov_b32_e32 v26, v48
	v_mov_b32_e32 v27, v48
	v_mov_b32_e32 v28, v48
	v_mov_b32_e32 v29, v48
	v_mov_b32_e32 v30, v48
	v_mov_b32_e32 v31, v48
	s_waitcnt vmcnt(0)
	ds_write_b128 v173, v[132:135]
	s_and_saveexec_b64 s[10:11], s[6:7]
	ds_write_b128 v182, v[128:131]
	s_or_b64 exec, exec, s[10:11]
	ds_read_b128 v[216:219], v181 offset:13312
	ds_read_b128 v[220:223], v181 offset:19968
	ds_read_b128 v[224:227], v181 offset:13344
	ds_read_b128 v[228:231], v181 offset:20000
	ds_read_b128 v[236:239], v181 offset:13376
	ds_read_b128 v[240:243], v181 offset:20032
	ds_read_b128 v[244:247], v181 offset:13408
	ds_read_b128 v[248:251], v181 offset:20064
	ds_read_b128 v[68:71], v181 offset:13440
	ds_read_b128 v[196:199], v181 offset:20096
	ds_read_b128 v[200:203], v181 offset:13472
	ds_read_b128 v[208:211], v181 offset:20128
	v_add_co_u32_e32 v32, vcc, 0x36000, v160
	s_nop 1
	v_addc_co_u32_e32 v33, vcc, 0, v161, vcc
	s_waitcnt lgkmcnt(12)
	global_load_dwordx4 v[132:135], v[32:33], off
	s_and_saveexec_b64 s[10:11], s[6:7]
	s_cbranch_execz .Lmla_entry_k1
	v_add_co_u32_e32 v32, vcc, 0x36000, v162
	s_nop 1
	v_addc_co_u32_e32 v33, vcc, 0, v163, vcc
	global_load_dwordx4 v[128:131], v[32:33], off
.Lmla_entry_k1:
	s_or_b64 exec, exec, s[10:11]
	v_add_co_u32_e32 v32, vcc, 0x18000, v158
	s_nop 1
	v_addc_co_u32_e32 v33, vcc, 0, v159, vcc
	global_load_dwordx4 v[136:139], v[32:33], off
	s_waitcnt lgkmcnt(0)
	s_barrier
; #define LAS __attribute__((address_space(3)))
; template <int DK, int PAR, bool HASNEXT, bool LDK, bool LDV, bool STK> ...
;     ...
;     LAS unsigned char* Kb = lds + ((PAR ^ 1) * A::KBUF);
;     LAS unsigned char* Vb = lds + 2 * A::KBUF + PAR * A::VBUF;
;     __builtin_amdgcn_s_setprio(1);
;     if (LDK) { ldk0 = *(const u32x4*)(kg0 + (size_t)(t + 3) * kstep); if (has1) ldk1 = *(const u32x4*)(kg1 + (size_t)(t + 3) * kstep); }
;     if (LDV) ldv = *(const u32x4*)(vg + (size_t)(t + 2) * vstep);
;     bf16x8 kf[A::NDS][2];
;     if (HASNEXT) {
; #pragma unroll
;         for (int ds = 0; ds < A::NDS; ++ds) {
;             kf[ds][0] = *(const LAS bf16x8*)(Kb + aoffk + ds * 32);
;             kf[ds][1] = *(const LAS bf16x8*)(Kb + aoffk + 32 * A::KSTR + ds * 32);
;         }
;     }
;     s16x4 vlo[4][2], vhi[4][2];
; #pragma unroll
;     for (int j = 0; j < 2; ++j) {
;         vlo[j][0] = vtr(Vb + aoffv + j * 16 * A::VSTR); vhi[j][0] = vtr(Vb + aoffv + (j * 16 + 8) * A::VSTR);
;         vlo[j][1] = vtr(Vb + aoffv + j * 16 * A::VSTR + 64); vhi[j][1] = vtr(Vb + aoffv + (j * 16 + 8) * A::VSTR + 64);
;     }
;     if (HASNEXT) {
;         f32x16 z;
; #pragma unroll
;         for (int i = 0; i < 16; ++i) z[i] = 0.f;
; #pragma unroll
;         for (int ds = 0; ds < A::NDS; ++ds) {
;             N0 = __builtin_amdgcn_mfma_f32_32x32x16_bf16(kf[ds][0], qf[ds], ds == 0 ? z : N0, 0, 0, 0);
;             N1 = __builtin_amdgcn_mfma_f32_32x32x16_bf16(kf[ds][1], qf[ds], ds == 0 ? z : N1, 0, 0, 0);
;         }
;     }
; #pragma unroll
;     for (int i = 0; i < 16; ++i) { l += C0[i]; l += C1[i]; }
;     bf16x8 pb[4];
;     { u32x4 w;
;       w.x = pk2(C0[0], C0[1]); w.y = pk2(C0[2], C0[3]); w.z = pk2(C0[4], C0[5]); w.w = pk2(C0[6], C0[7]); pb[0] = __builtin_bit_cast(bf16x8, w);
;       w.x = pk2(C0[8], C0[9]); w.y = pk2(C0[10], C0[11]); w.z = pk2(C0[12], C0[13]); w.w = pk2(C0[14], C0[15]); pb[1] = __builtin_bit_cast(bf16x8, w);
;       w.x = pk2(C1[0], C1[1]); w.y = pk2(C1[2], C1[3]); w.z = pk2(C1[4], C1[5]); w.w = pk2(C1[6], C1[7]); pb[2] = __builtin_bit_cast(bf16x8, w);
;       w.x = pk2(C1[8], C1[9]); w.y = pk2(C1[10], C1[11]); w.z = pk2(C1[12], C1[13]); w.w = pk2(C1[14], C1[15]); pb[3] = __builtin_bit_cast(bf16x8, w); }
;     if (HASNEXT) {
;         constexpr int VPER = (DK == 64) ? 6 : 4;
; #pragma unroll
.LBB0_763:
	s_setprio 1
	v_mfma_f32_32x32x16_bf16 v[32:47], v[216:219], v[120:123], 0
	v_lshl_add_u64 v[66:67], s[50:51], 0, v[164:165]
	v_add_co_u32_e32 v94, vcc, 0x2a5a8000, v66
	v_lshl_add_u64 v[64:65], s[50:51], 0, v[166:167]
	s_nop 0
	v_addc_co_u32_e32 v95, vcc, 0, v67, vcc
	global_load_dwordx4 v[140:143], v[94:95], off
	s_and_saveexec_b64 s[10:11], s[6:7]
	s_cbranch_execz .LBB0_765
	v_add_co_u32_e32 v94, vcc, 0x2a5a8000, v64
	s_nop 1
	v_addc_co_u32_e32 v95, vcc, 0, v65, vcc
	global_load_dwordx4 v[124:127], v[94:95], off
.LBB0_765:
	s_or_b64 exec, exec, s[10:11]
	ds_read_b64_tr_b16 v[204:205], v172 offset:26624
	ds_read_b64_tr_b16 v[206:207], v172 offset:28160
	ds_read_b64_tr_b16 v[212:213], v172 offset:29696
	ds_read_b64_tr_b16 v[214:215], v172 offset:31232
	v_lshl_add_u64 v[80:81], s[50:51], 0, v[168:169]
	v_add_co_u32_e32 v94, vcc, 0x14f30000, v80
	v_add_f32_e32 v96, v185, v48
	s_nop 0
	v_addc_co_u32_e32 v95, vcc, 0, v81, vcc
	global_load_dwordx4 v[144:147], v[94:95], off offset:128
	v_mfma_f32_32x32x16_bf16 v[48:63], v[220:223], v[120:123], 0
	v_add_f32_e32 v96, v183, v96
	v_add_f32_e32 v96, v187, v96
	v_add_f32_e32 v96, v184, v96
	v_add_f32_e32 v96, v186, v96
	v_mfma_f32_32x32x16_bf16 v[32:47], v[224:227], v[116:119], v[32:47]
	v_add_f32_e32 v96, v82, v96
	v_add_f32_e32 v96, v189, v96
	v_add_f32_e32 v96, v83, v96
	v_add_f32_e32 v96, v188, v96
	v_mfma_f32_32x32x16_bf16 v[48:63], v[228:231], v[116:119], v[48:63]
	s_waitcnt vmcnt(3)
	ds_write_b128 v173, v[132:135] offset:13312
	s_and_saveexec_b64 s[10:11], s[6:7]
	ds_write_b128 v182, v[128:131] offset:13312
	s_or_b64 exec, exec, s[10:11]
	s_waitcnt vmcnt(2)
	ds_write_b128 v170, v[136:139] offset:38912
	v_add_f32_e32 v94, v84, v96
	v_add_f32_e32 v94, v190, v94
	v_add_f32_e32 v94, v85, v94
	v_add_f32_e32 v94, v192, v94
	v_mfma_f32_32x32x16_bf16 v[32:47], v[236:239], v[112:115], v[32:47]
	v_add_f32_e32 v94, v86, v94
	v_add_f32_e32 v94, v194, v94
	v_add_f32_e32 v94, v87, v94
	v_add_f32_e32 v94, v191, v94
	v_mfma_f32_32x32x16_bf16 v[48:63], v[240:243], v[112:115], v[48:63]
	v_add_f32_e32 v94, v72, v94
	v_add_f32_e32 v94, v193, v94
	v_add_f32_e32 v94, v73, v94
	v_add_f32_e32 v94, v88, v94
	v_mfma_f32_32x32x16_bf16 v[32:47], v[244:247], v[108:111], v[32:47]
	v_add_f32_e32 v94, v74, v94
	v_add_f32_e32 v94, v90, v94
	v_add_f32_e32 v94, v75, v94
	v_add_f32_e32 v94, v89, v94
	v_mfma_f32_32x32x16_bf16 v[48:63], v[248:251], v[108:111], v[48:63]
	v_add_f32_e32 v94, v76, v94
	v_add_f32_e32 v94, v91, v94
	v_add_f32_e32 v94, v77, v94
	v_add_f32_e32 v94, v92, v94
	v_mfma_f32_32x32x16_bf16 v[32:47], v[68:71], v[104:107], v[32:47]
	v_add_f32_e32 v94, v78, v94
	v_add_f32_e32 v94, v93, v94
	v_add_f32_e32 v94, v79, v94
	v_cvt_pk_bf16_f32 v216, v185, v187
	v_mfma_f32_32x32x16_bf16 v[48:63], v[196:199], v[104:107], v[48:63]
	v_cvt_pk_bf16_f32 v217, v186, v189
	v_cvt_pk_bf16_f32 v218, v188, v190
	v_cvt_pk_bf16_f32 v219, v192, v194
	v_cvt_pk_bf16_f32 v186, v191, v193
	ds_read_b64_tr_b16 v[196:197], v172 offset:26688
	ds_read_b64_tr_b16 v[198:199], v172 offset:28224
	ds_read_b64_tr_b16 v[190:191], v172 offset:29760
	v_mfma_f32_32x32x16_bf16 v[32:47], v[200:203], v[100:103], v[32:47]
	v_cvt_pk_bf16_f32 v187, v88, v90
	v_cvt_pk_bf16_f32 v188, v89, v91
	v_cvt_pk_bf16_f32 v189, v92, v93
	v_cvt_pk_bf16_f32 v88, v183, v184
	ds_read_b64_tr_b16 v[192:193], v172 offset:31296
	v_mfma_f32_32x32x16_bf16 v[48:63], v[208:211], v[100:103], v[48:63]
	v_cvt_pk_bf16_f32 v89, v82, v83
	v_cvt_pk_bf16_f32 v90, v84, v85
	v_cvt_pk_bf16_f32 v91, v86, v87
	v_cvt_pk_bf16_f32 v68, v72, v73
	v_cvt_pk_bf16_f32 v69, v74, v75
	v_cvt_pk_bf16_f32 v70, v76, v77
	v_cvt_pk_bf16_f32 v71, v78, v79
	s_waitcnt lgkmcnt(9)
	v_mfma_f32_32x32x16_bf16 v[16:31], v[204:207], v[216:219], v[16:31]
	ds_read_b64_tr_b16 v[72:73], v172 offset:32768
	ds_read_b64_tr_b16 v[74:75], v172 offset:34304
	ds_read_b64_tr_b16 v[76:77], v172 offset:32832
	ds_read_b64_tr_b16 v[78:79], v172 offset:34368
	v_exp_f32_e32 v96, v32
	v_exp_f32_e32 v99, v33
	v_exp_f32_e32 v150, v34
	v_exp_f32_e32 v152, v35
	s_waitcnt lgkmcnt(6)
	v_mfma_f32_32x32x16_bf16 v[0:15], v[196:199], v[216:219], v[0:15]
	v_exp_f32_e32 v154, v36
	v_exp_f32_e32 v184, v39
	v_exp_f32_e32 v185, v40
	v_exp_f32_e32 v195, v47
	v_mfma_f32_32x32x16_bf16 v[16:31], v[212:215], v[186:189], v[16:31]
	v_exp_f32_e32 v155, v52
	v_exp_f32_e32 v52, v37
	v_exp_f32_e32 v180, v53
	v_exp_f32_e32 v53, v38
	s_waitcnt lgkmcnt(4)
	v_mfma_f32_32x32x16_bf16 v[0:15], v[190:193], v[186:189], v[0:15]
	ds_read_b128 v[216:219], v181
	ds_read_b128 v[220:223], v181 offset:6656
	ds_read_b128 v[224:227], v181 offset:32
	v_exp_f32_e32 v98, v48
	v_exp_f32_e32 v49, v49
	v_exp_f32_e32 v151, v50
	v_exp_f32_e32 v153, v51
	s_waitcnt lgkmcnt(5)
	v_mfma_f32_32x32x16_bf16 v[16:31], v[72:75], v[88:91], v[16:31]
	ds_read_b64_tr_b16 v[72:73], v172 offset:35840
	ds_read_b64_tr_b16 v[74:75], v172 offset:37376
	ds_read_b128 v[228:231], v181 offset:6688
	ds_read_b128 v[236:239], v181 offset:64
	ds_read_b128 v[240:243], v181 offset:6720
	v_exp_f32_e32 v183, v54
	v_exp_f32_e32 v187, v55
	v_exp_f32_e32 v188, v56
	v_exp_f32_e32 v56, v41
	s_waitcnt lgkmcnt(8)
	v_mfma_f32_32x32x16_bf16 v[0:15], v[76:79], v[88:91], v[0:15]
	ds_read_b64_tr_b16 v[76:77], v172 offset:35904
	ds_read_b64_tr_b16 v[78:79], v172 offset:37440
	ds_read_b128 v[244:247], v181 offset:96
	ds_read_b128 v[248:251], v181 offset:6752
	ds_read_b128 v[32:35], v181 offset:128
	v_exp_f32_e32 v189, v57
	v_exp_f32_e32 v57, v42
	v_exp_f32_e32 v190, v58
	v_exp_f32_e32 v186, v43
	s_waitcnt lgkmcnt(8)
	v_mfma_f32_32x32x16_bf16 v[16:31], v[72:75], v[68:71], v[16:31]
	ds_read_b128 v[36:39], v181 offset:6784
	ds_read_b128 v[196:199], v181 offset:160
	ds_read_b128 v[200:203], v181 offset:6816
	v_exp_f32_e32 v191, v59
	v_exp_f32_e32 v192, v44
	v_exp_f32_e32 v193, v60
	v_exp_f32_e32 v60, v45
	s_waitcnt lgkmcnt(6)
	v_mfma_f32_32x32x16_bf16 v[0:15], v[76:79], v[68:71], v[0:15]
	v_exp_f32_e32 v194, v61
	v_exp_f32_e32 v61, v46
	v_exp_f32_e32 v62, v62
	v_exp_f32_e32 v63, v63
	s_setprio 0
	s_waitcnt lgkmcnt(0)
	s_barrier
	s_setprio 1
	v_add_co_u32_e32 v66, vcc, 0x2a5ba000, v66
	s_nop 1
	v_addc_co_u32_e32 v67, vcc, 0, v67, vcc
	global_load_dwordx4 v[132:135], v[66:67], off
	s_and_saveexec_b64 s[10:11], s[6:7]
	s_cbranch_execz .LBB0_769
	v_add_co_u32_e32 v64, vcc, 0x2a5ba000, v64
	s_nop 1
	v_addc_co_u32_e32 v65, vcc, 0, v65, vcc
	global_load_dwordx4 v[128:131], v[64:65], off
; #define LAS __attribute__((address_space(3)))
; template <int DK, int PAR, bool HASNEXT, bool LDK, bool LDV, bool STK> ...
;     ...
;     LAS unsigned char* Kb = lds + ((PAR ^ 1) * A::KBUF);
;     LAS unsigned char* Vb = lds + 2 * A::KBUF + PAR * A::VBUF;
;     __builtin_amdgcn_s_setprio(1);
;     if (LDK) { ldk0 = *(const u32x4*)(kg0 + (size_t)(t + 3) * kstep); if (has1) ldk1 = *(const u32x4*)(kg1 + (size_t)(t + 3) * kstep); }
;     if (LDV) ldv = *(const u32x4*)(vg + (size_t)(t + 2) * vstep);
;     bf16x8 kf[A::NDS][2];
;     if (HASNEXT) {
; #pragma unroll
;         for (int ds = 0; ds < A::NDS; ++ds) {
;             kf[ds][0] = *(const LAS bf16x8*)(Kb + aoffk + ds * 32);
;             kf[ds][1] = *(const LAS bf16x8*)(Kb + aoffk + 32 * A::KSTR + ds * 32);
;         }
;     }
;     s16x4 vlo[4][2], vhi[4][2];
; #pragma unroll
;     for (int j = 0; j < 2; ++j) {
;         vlo[j][0] = vtr(Vb + aoffv + j * 16 * A::VSTR); vhi[j][0] = vtr(Vb + aoffv + (j * 16 + 8) * A::VSTR);
;         vlo[j][1] = vtr(Vb + aoffv + j * 16 * A::VSTR + 64); vhi[j][1] = vtr(Vb + aoffv + (j * 16 + 8) * A::VSTR + 64);
;     }
;     if (HASNEXT) {
;         f32x16 z;
; #pragma unroll
;         for (int i = 0; i < 16; ++i) z[i] = 0.f;
; #pragma unroll
;         for (int ds = 0; ds < A::NDS; ++ds) {
;             N0 = __builtin_amdgcn_mfma_f32_32x32x16_bf16(kf[ds][0], qf[ds], ds == 0 ? z : N0, 0, 0, 0);
;             N1 = __builtin_amdgcn_mfma_f32_32x32x16_bf16(kf[ds][1], qf[ds], ds == 0 ? z : N1, 0, 0, 0);
;         }
;     }
; #pragma unroll
;     for (int i = 0; i < 16; ++i) { l += C0[i]; l += C1[i]; }
;     bf16x8 pb[4];
;     { u32x4 w;
;       w.x = pk2(C0[0], C0[1]); w.y = pk2(C0[2], C0[3]); w.z = pk2(C0[4], C0[5]); w.w = pk2(C0[6], C0[7]); pb[0] = __builtin_bit_cast(bf16x8, w);
;       w.x = pk2(C0[8], C0[9]); w.y = pk2(C0[10], C0[11]); w.z = pk2(C0[12], C0[13]); w.w = pk2(C0[14], C0[15]); pb[1] = __builtin_bit_cast(bf16x8, w);
;       w.x = pk2(C1[0], C1[1]); w.y = pk2(C1[2], C1[3]); w.z = pk2(C1[4], C1[5]); w.w = pk2(C1[6], C1[7]); pb[2] = __builtin_bit_cast(bf16x8, w);
;       w.x = pk2(C1[8], C1[9]); w.y = pk2(C1[10], C1[11]); w.z = pk2(C1[12], C1[13]); w.w = pk2(C1[14], C1[15]); pb[3] = __builtin_bit_cast(bf16x8, w); }
;     if (HASNEXT) {
;         constexpr int VPER = (DK == 64) ? 6 : 4;
; #pragma unroll
.LBB0_769:
	s_or_b64 exec, exec, s[10:11]
	s_mov_b32 s10, 0x14f48000
	v_mfma_f32_32x32x16_bf16 v[64:79], v[216:219], v[120:123], 0
	v_add_co_u32_e32 v40, vcc, s10, v80
	s_nop 0
	v_addc_co_u32_e32 v41, vcc, 0, v81, vcc
	global_load_dwordx4 v[136:139], v[40:41], off offset:128
	v_add_f32_e32 v48, v96, v94
	v_add_f32_e32 v48, v98, v48
	v_mfma_f32_32x32x16_bf16 v[80:95], v[220:223], v[120:123], 0
	v_add_f32_e32 v40, v99, v48
	v_add_f32_e32 v40, v49, v40
	v_add_f32_e32 v40, v150, v40
	v_add_f32_e32 v40, v151, v40
	v_mfma_f32_32x32x16_bf16 v[64:79], v[224:227], v[116:119], v[64:79]
	v_add_f32_e32 v40, v152, v40
	v_add_f32_e32 v40, v153, v40
	v_add_f32_e32 v40, v154, v40
	v_add_f32_e32 v40, v155, v40
	v_mfma_f32_32x32x16_bf16 v[80:95], v[228:231], v[116:119], v[80:95]
	s_waitcnt vmcnt(3)
	ds_write_b128 v173, v[140:143]
	s_and_saveexec_b64 s[10:11], s[6:7]
	ds_write_b128 v182, v[124:127]
	s_or_b64 exec, exec, s[10:11]
	s_waitcnt vmcnt(2)
	ds_write_b128 v170, v[144:147] offset:26624
	v_add_f32_e32 v40, v52, v40
	v_add_f32_e32 v40, v180, v40
	v_add_f32_e32 v40, v53, v40
	v_add_f32_e32 v40, v183, v40
	v_mfma_f32_32x32x16_bf16 v[64:79], v[236:239], v[112:115], v[64:79]
	v_add_f32_e32 v40, v184, v40
	v_add_f32_e32 v40, v187, v40
	v_add_f32_e32 v40, v185, v40
	v_add_f32_e32 v40, v188, v40
	v_mfma_f32_32x32x16_bf16 v[80:95], v[240:243], v[112:115], v[80:95]
	v_add_f32_e32 v40, v56, v40
	v_add_f32_e32 v40, v189, v40
	v_add_f32_e32 v40, v57, v40
	v_add_f32_e32 v40, v190, v40
	v_mfma_f32_32x32x16_bf16 v[64:79], v[244:247], v[108:111], v[64:79]
	v_add_f32_e32 v40, v186, v40
	v_add_f32_e32 v40, v191, v40
	v_add_f32_e32 v40, v192, v40
	v_add_f32_e32 v44, v193, v40
	v_mfma_f32_32x32x16_bf16 v[80:95], v[248:251], v[108:111], v[80:95]
	v_add_f32_e32 v44, v60, v44
	v_add_f32_e32 v44, v194, v44
	v_add_f32_e32 v44, v61, v44
	v_add_f32_e32 v48, v62, v44
	v_mfma_f32_32x32x16_bf16 v[64:79], v[32:35], v[104:107], v[64:79]
	v_add_f32_e32 v48, v195, v48
	v_add_f32_e32 v48, v63, v48
	v_cvt_pk_bf16_f32 v50, v96, v99
	v_cvt_pk_bf16_f32 v51, v150, v152
	ds_read_b64_tr_b16 v[44:45], v172 offset:38912
	ds_read_b64_tr_b16 v[46:47], v172 offset:40448
	v_mfma_f32_32x32x16_bf16 v[80:95], v[36:39], v[104:107], v[80:95]
	v_cvt_pk_bf16_f32 v52, v154, v52
	v_cvt_pk_bf16_f32 v53, v53, v184
	v_cvt_pk_bf16_f32 v58, v185, v56
	v_cvt_pk_bf16_f32 v59, v57, v186
	ds_read_b64_tr_b16 v[36:37], v172 offset:38976
	ds_read_b64_tr_b16 v[38:39], v172 offset:40512
	ds_read_b64_tr_b16 v[54:55], v172 offset:41984
	v_mfma_f32_32x32x16_bf16 v[64:79], v[196:199], v[100:103], v[64:79]
	v_cvt_pk_bf16_f32 v60, v192, v60
	v_cvt_pk_bf16_f32 v61, v61, v195
	v_cvt_pk_bf16_f32 v184, v98, v49
	v_cvt_pk_bf16_f32 v185, v151, v153
	ds_read_b64_tr_b16 v[56:57], v172 offset:43520
	ds_read_b64_tr_b16 v[40:41], v172 offset:42048
	ds_read_b64_tr_b16 v[42:43], v172 offset:43584
	v_mfma_f32_32x32x16_bf16 v[80:95], v[200:203], v[100:103], v[80:95]
	v_cvt_pk_bf16_f32 v186, v155, v180
	v_cvt_pk_bf16_f32 v187, v183, v187
	v_cvt_pk_bf16_f32 v32, v188, v189
	v_cvt_pk_bf16_f32 v33, v190, v191
	v_cvt_pk_bf16_f32 v34, v193, v194
	v_cvt_pk_bf16_f32 v35, v62, v63
	s_waitcnt lgkmcnt(6)
	v_mfma_f32_32x32x16_bf16 v[16:31], v[44:47], v[50:53], v[16:31]
	v_exp_f32_e32 v189, v67
	v_exp_f32_e32 v188, v68
	v_exp_f32_e32 v190, v69
	v_exp_f32_e32 v192, v70
	s_waitcnt lgkmcnt(4)
	v_mfma_f32_32x32x16_bf16 v[0:15], v[36:39], v[50:53], v[0:15]
	ds_read_b64_tr_b16 v[36:37], v172 offset:45056
	ds_read_b64_tr_b16 v[38:39], v172 offset:46592
	v_exp_f32_e32 v194, v71
	v_exp_f32_e32 v191, v72
	v_exp_f32_e32 v193, v73
	v_exp_f32_e32 v183, v80
	s_waitcnt lgkmcnt(4)
	v_mfma_f32_32x32x16_bf16 v[16:31], v[54:57], v[58:61], v[16:31]
	v_exp_f32_e32 v82, v82
	v_exp_f32_e32 v83, v83
	v_exp_f32_e32 v84, v84
	v_exp_f32_e32 v85, v85
	s_waitcnt lgkmcnt(2)
	v_mfma_f32_32x32x16_bf16 v[0:15], v[40:43], v[58:61], v[0:15]
	ds_read_b64_tr_b16 v[40:41], v172 offset:45120
	ds_read_b64_tr_b16 v[42:43], v172 offset:46656
	ds_read_b128 v[216:219], v181 offset:13312
	ds_read_b128 v[220:223], v181 offset:19968
	ds_read_b128 v[224:227], v181 offset:13344
	v_exp_f32_e32 v86, v86
	v_exp_f32_e32 v87, v87
	v_exp_f32_e32 v72, v88
	v_exp_f32_e32 v73, v89
	s_waitcnt lgkmcnt(5)
	v_mfma_f32_32x32x16_bf16 v[16:31], v[36:39], v[184:187], v[16:31]
	ds_read_b64_tr_b16 v[36:37], v172 offset:48128
	ds_read_b64_tr_b16 v[38:39], v172 offset:49664
	ds_read_b128 v[228:231], v181 offset:20000
	ds_read_b128 v[236:239], v181 offset:13376
	ds_read_b128 v[240:243], v181 offset:20032
	v_exp_f32_e32 v88, v74
	v_exp_f32_e32 v74, v90
	v_exp_f32_e32 v90, v75
	v_exp_f32_e32 v75, v91
	s_waitcnt lgkmcnt(8)
	v_mfma_f32_32x32x16_bf16 v[0:15], v[40:43], v[184:187], v[0:15]
	ds_read_b64_tr_b16 v[40:41], v172 offset:48192
	ds_read_b64_tr_b16 v[42:43], v172 offset:49728
	ds_read_b128 v[244:247], v181 offset:13408
	ds_read_b128 v[248:251], v181 offset:20064
	ds_read_b128 v[68:71], v181 offset:13440
	v_exp_f32_e32 v89, v76
	v_exp_f32_e32 v76, v92
	v_exp_f32_e32 v91, v77
	v_exp_f32_e32 v77, v93
	s_waitcnt lgkmcnt(8)
	v_mfma_f32_32x32x16_bf16 v[16:31], v[36:39], v[32:35], v[16:31]
	ds_read_b128 v[196:199], v181 offset:20096
	ds_read_b128 v[200:203], v181 offset:13472
	ds_read_b128 v[208:211], v181 offset:20128
	v_exp_f32_e32 v92, v78
	v_exp_f32_e32 v78, v94
	v_exp_f32_e32 v93, v79
	v_exp_f32_e32 v79, v95
	s_waitcnt lgkmcnt(6)
	v_mfma_f32_32x32x16_bf16 v[0:15], v[40:43], v[32:35], v[0:15]
	v_exp_f32_e32 v185, v64
	v_exp_f32_e32 v187, v65
	v_exp_f32_e32 v184, v81
	v_exp_f32_e32 v186, v66
	s_setprio 0
	s_waitcnt lgkmcnt(0)
	s_barrier
	s_add_i32 s12, s12, 2
	s_mov_b64 s[10:11], 0x30000
	v_lshl_add_u64 v[164:165], v[164:165], 0, s[72:73]
	v_lshl_add_u64 v[166:167], v[166:167], 0, s[72:73]
	s_cmpk_lt_u32 s12, 0x7e
	v_lshl_add_u64 v[168:169], v[168:169], 0, s[10:11]
	s_cbranch_scc1 .LBB0_763
	s_branch .LBB0_781

; template <int DK, int PAR, bool HASNEXT, bool LDK, bool LDV, bool STK> ...
;     ...
;     __builtin_amdgcn_s_setprio(1);
;     if (LDK) { ldk0 = *(const u32x4*)(kg0 + (size_t)(t + 3) * kstep); if (has1) ldk1 = *(const u32x4*)(kg1 + (size_t)(t + 3) * kstep); }
;     if (LDV) ldv = *(const u32x4*)(vg + (size_t)(t + 2) * vstep);
; template <int DK>
; __device__ __forceinline__ void attn_unit(LAS unsigned char* lds, const bf16_t* Qp, int qpitch, const bf16_t* Kp, int kpitch, const bf16_t* Vp, int vpitch, bf16_t* Op, int nt) {
;     ...
;     attn_step<DK, 0, true, true, true, true>(ATT_EVEN(cA0, cA1, cB0, cB1, t));
.LBB0_781:
	s_waitcnt vmcnt(0)
	ds_read_b128 v[132:135], v173
	s_and_saveexec_b64 s[10:11], s[6:7]
	ds_read_b128 v[128:131], v182
	s_or_b64 exec, exec, s[10:11]
	s_waitcnt lgkmcnt(0)
	s_setprio 1
	v_add_co_u32_e32 v32, vcc, 0x936000, v160
	s_nop 1
	v_addc_co_u32_e32 v33, vcc, 0, v161, vcc
	global_load_dwordx4 v[64:67], v[32:33], off
	s_and_saveexec_b64 s[10:11], s[6:7]
	s_cbranch_execz .LBB0_783
	v_add_co_u32_e32 v32, vcc, 0x936000, v162
	s_nop 1
	v_addc_co_u32_e32 v33, vcc, 0, v163, vcc
	global_load_dwordx4 v[124:127], v[32:33], off
